# w_up conversion writes whole 1KB LDS-image blocks per store (remapped LDS transpose reads); up-GEMM linear B staging
# speedup vs baseline: 1.0096x; 1.0096x over previous
.LBB0_327:
	s_andn2_b64 vcc, exec, s[16:17]
	s_cbranch_vccnz .LBB0_329
	s_add_i32 s16, s20, 0xffffe500
	s_lshr_b32 s16, s16, 2
	s_and_b32 s17, s16, 0x3fffffc0
	s_lshl_b32 s16, s20, 5
	s_and_b32 s16, s16, 0x1fe0
	v_add_u32_e32 v20, s17, v1
	s_lshl_b32 s90, s16, 2
	v_ashrrev_i32_e32 v21, 31, v20
	v_lshl_add_u64 v[22:23], v[6:7], 0, s[90:91]
	v_lshlrev_b64 v[20:21], 15, v[20:21]
	v_lshl_add_u64 v[20:21], v[22:23], 0, v[20:21]
	v_add_co_u32_e32 v22, vcc, 0x10000, v20
	global_load_dword v9, v[20:21], off nt
	s_nop 0
	v_addc_co_u32_e32 v23, vcc, 0, v21, vcc
	global_load_dword v18, v[22:23], off nt
	v_add_co_u32_e32 v22, vcc, 0x20000, v20
	s_lshl_b32 s90, s17, 1
	s_nop 0
	v_addc_co_u32_e32 v23, vcc, 0, v21, vcc
	global_load_dword v30, v[22:23], off nt
	v_add_co_u32_e32 v22, vcc, 0x30000, v20
	s_nop 1
	v_addc_co_u32_e32 v23, vcc, 0, v21, vcc
	global_load_dword v31, v[22:23], off nt
	v_add_co_u32_e32 v22, vcc, 0x40000, v20
	s_nop 1
	v_addc_co_u32_e32 v23, vcc, 0, v21, vcc
	global_load_dword v32, v[22:23], off nt
	v_add_co_u32_e32 v22, vcc, 0x50000, v20
	s_nop 1
	v_addc_co_u32_e32 v23, vcc, 0, v21, vcc
	global_load_dword v33, v[22:23], off nt
	v_add_co_u32_e32 v22, vcc, 0x60000, v20
	s_nop 1
	v_addc_co_u32_e32 v23, vcc, 0, v21, vcc
	global_load_dword v34, v[22:23], off nt
	v_add_co_u32_e32 v22, vcc, 0x70000, v20
	s_nop 1
	v_addc_co_u32_e32 v23, vcc, 0, v21, vcc
	global_load_dword v35, v[22:23], off nt
	v_add_co_u32_e32 v22, vcc, 0x80000, v20
	s_nop 1
	v_addc_co_u32_e32 v23, vcc, 0, v21, vcc
	global_load_dword v36, v[22:23], off nt
	v_add_co_u32_e32 v22, vcc, 0x90000, v20
	s_nop 1
	v_addc_co_u32_e32 v23, vcc, 0, v21, vcc
	global_load_dword v37, v[22:23], off nt
	v_add_co_u32_e32 v22, vcc, 0xa0000, v20
	s_nop 1
	v_addc_co_u32_e32 v23, vcc, 0, v21, vcc
	global_load_dword v38, v[22:23], off nt
	v_add_co_u32_e32 v22, vcc, 0xb0000, v20
	s_nop 1
	v_addc_co_u32_e32 v23, vcc, 0, v21, vcc
	global_load_dword v39, v[22:23], off nt
	v_add_co_u32_e32 v22, vcc, 0xc0000, v20
	s_nop 1
	v_addc_co_u32_e32 v23, vcc, 0, v21, vcc
	global_load_dword v40, v[22:23], off nt
	v_add_co_u32_e32 v22, vcc, 0xd0000, v20
	s_nop 1
	v_addc_co_u32_e32 v23, vcc, 0, v21, vcc
	global_load_dword v41, v[22:23], off nt
	v_add_co_u32_e32 v22, vcc, 0xe0000, v20
	s_nop 1
	v_addc_co_u32_e32 v23, vcc, 0, v21, vcc
	global_load_dword v42, v[22:23], off nt
	v_add_co_u32_e32 v22, vcc, 0xf0000, v20
	s_nop 1
	v_addc_co_u32_e32 v23, vcc, 0, v21, vcc
	global_load_dword v43, v[22:23], off nt
	v_add_co_u32_e32 v22, vcc, 0x100000, v20
	s_nop 1
	v_addc_co_u32_e32 v23, vcc, 0, v21, vcc
	global_load_dword v44, v[22:23], off nt
	v_add_co_u32_e32 v22, vcc, 0x110000, v20
	s_nop 1
	v_addc_co_u32_e32 v23, vcc, 0, v21, vcc
	global_load_dword v45, v[22:23], off nt
	v_add_co_u32_e32 v22, vcc, 0x120000, v20
	s_nop 1
	v_addc_co_u32_e32 v23, vcc, 0, v21, vcc
	global_load_dword v46, v[22:23], off nt
	v_add_co_u32_e32 v22, vcc, 0x130000, v20
	s_nop 1
	v_addc_co_u32_e32 v23, vcc, 0, v21, vcc
	global_load_dword v47, v[22:23], off nt
	v_add_co_u32_e32 v22, vcc, 0x140000, v20
	s_nop 1
	v_addc_co_u32_e32 v23, vcc, 0, v21, vcc
	global_load_dword v48, v[22:23], off nt
	v_add_co_u32_e32 v22, vcc, 0x150000, v20
	s_nop 1
	v_addc_co_u32_e32 v23, vcc, 0, v21, vcc
	global_load_dword v49, v[22:23], off nt
	v_add_co_u32_e32 v22, vcc, 0x160000, v20
	s_nop 1
	v_addc_co_u32_e32 v23, vcc, 0, v21, vcc
	global_load_dword v50, v[22:23], off nt
	v_add_co_u32_e32 v22, vcc, 0x170000, v20
	s_nop 1
	v_addc_co_u32_e32 v23, vcc, 0, v21, vcc
	global_load_dword v51, v[22:23], off nt
	v_add_co_u32_e32 v22, vcc, 0x180000, v20
	s_nop 1
	v_addc_co_u32_e32 v23, vcc, 0, v21, vcc
	global_load_dword v52, v[22:23], off nt
	v_add_co_u32_e32 v22, vcc, 0x190000, v20
	s_nop 1
	v_addc_co_u32_e32 v23, vcc, 0, v21, vcc
	global_load_dword v53, v[22:23], off nt
	v_add_co_u32_e32 v22, vcc, 0x1a0000, v20
	s_nop 1
	v_addc_co_u32_e32 v23, vcc, 0, v21, vcc
	global_load_dword v54, v[22:23], off nt
	v_add_co_u32_e32 v22, vcc, 0x1b0000, v20
	s_nop 1
	v_addc_co_u32_e32 v23, vcc, 0, v21, vcc
	global_load_dword v55, v[22:23], off nt
	v_add_co_u32_e32 v22, vcc, 0x1c0000, v20
	s_nop 1
	v_addc_co_u32_e32 v23, vcc, 0, v21, vcc
	global_load_dword v56, v[22:23], off nt
	v_add_co_u32_e32 v22, vcc, 0x1d0000, v20
	s_nop 1
	v_addc_co_u32_e32 v23, vcc, 0, v21, vcc
	global_load_dword v57, v[22:23], off nt
	v_add_co_u32_e32 v22, vcc, 0x1e0000, v20
	s_nop 1
	v_addc_co_u32_e32 v23, vcc, 0, v21, vcc
	v_add_co_u32_e32 v20, vcc, 0x1f0000, v20
	global_load_dword v22, v[22:23], off nt
	s_nop 0
	v_addc_co_u32_e32 v21, vcc, 0, v21, vcc
	global_load_dword v20, v[20:21], off nt
	s_waitcnt vmcnt(0)
	ds_write2_b32 v24, v9, v18 offset1:66
	ds_write2_b32 v24, v30, v31 offset0:132 offset1:198
	v_add_u32_e32 v9, 0x400, v24
	ds_write2_b32 v9, v32, v33 offset0:8 offset1:74
	ds_write2_b32 v9, v34, v35 offset0:140 offset1:206
	v_add_u32_e32 v9, 0x800, v24
	ds_write2_b32 v9, v36, v37 offset0:16 offset1:82
	ds_write2_b32 v9, v38, v39 offset0:148 offset1:214
	v_add_u32_e32 v9, 0xc00, v24
	ds_write2_b32 v9, v40, v41 offset0:24 offset1:90
	ds_write2_b32 v9, v42, v43 offset0:156 offset1:222
	v_add_u32_e32 v9, 0x1000, v24
	ds_write2_b32 v9, v44, v45 offset0:32 offset1:98
	ds_write2_b32 v9, v46, v47 offset0:164 offset1:230
	v_add_u32_e32 v9, 0x1400, v24
	ds_write2_b32 v9, v48, v49 offset0:40 offset1:106
	ds_write2_b32 v9, v50, v51 offset0:172 offset1:238
	v_add_u32_e32 v9, 0x1800, v24
	ds_write2_b32 v9, v52, v53 offset0:48 offset1:114
	ds_write2_b32 v9, v54, v55 offset0:180 offset1:246
	v_add_u32_e32 v9, 0x1c00, v24
	ds_write2_b32 v9, v56, v57 offset0:56 offset1:122
	ds_write2_b32 v9, v22, v20 offset0:188 offset1:254
	s_waitcnt lgkmcnt(0)
	v_and_b32_e32 v70, 3, v146
	v_mul_u32_u24_e32 v70, 0x420, v70
	v_lshrrev_b32_e32 v71, 4, v146
	v_lshl_add_u32 v70, v71, 5, v70
	v_bfe_u32 v71, v146, 2, 2
	v_lshl_add_u32 v70, v71, 2, v70
	s_lshl_b32 s100, s49, 14
	v_add_u32_e32 v70, s100, v70
	v_add_u32_e32 v71, 0x1080, v70
	ds_read2_b32 v[22:23], v70 offset0:33 offset1:37
	ds_read2_b32 v[34:35], v70 offset1:4
	ds_read2_b32 v[36:37], v70 offset0:66 offset1:70
	ds_read2_b32 v[38:39], v70 offset0:99 offset1:103
	ds_read2_b32 v[40:41], v70 offset0:132 offset1:136
	ds_read2_b32 v[42:43], v70 offset0:165 offset1:169
	ds_read2_b32 v[44:45], v70 offset0:198 offset1:202
	ds_read2_b32 v[46:47], v70 offset0:231 offset1:235
	s_waitcnt lgkmcnt(7)
	v_bfe_u32 v18, v22, 16, 1
	s_waitcnt lgkmcnt(6)
	v_bfe_u32 v9, v34, 16, 1
	v_add3_u32 v9, v34, v9, s79
	v_lshrrev_b32_e32 v9, 16, v9
	v_add3_u32 v18, v22, v18, s79
	v_and_or_b32 v30, v18, s80, v9
	s_waitcnt lgkmcnt(5)
	v_bfe_u32 v9, v36, 16, 1
	v_add3_u32 v9, v36, v9, s79
	s_waitcnt lgkmcnt(4)
	v_bfe_u32 v18, v38, 16, 1
	v_lshrrev_b32_e32 v9, 16, v9
	v_add3_u32 v18, v38, v18, s79
	v_and_or_b32 v31, v18, s80, v9
	s_waitcnt lgkmcnt(3)
	v_bfe_u32 v9, v40, 16, 1
	v_add3_u32 v9, v40, v9, s79
	s_waitcnt lgkmcnt(2)
	v_bfe_u32 v18, v42, 16, 1
	v_lshrrev_b32_e32 v9, 16, v9
	v_add3_u32 v18, v42, v18, s79
	v_and_or_b32 v32, v18, s80, v9
	s_waitcnt lgkmcnt(1)
	v_bfe_u32 v9, v44, 16, 1
	v_add3_u32 v9, v44, v9, s79
	s_waitcnt lgkmcnt(0)
	v_bfe_u32 v18, v46, 16, 1
	v_lshrrev_b32_e32 v9, 16, v9
	v_add3_u32 v18, v46, v18, s79
	v_add_u32_e32 v48, s16, v25
	v_and_or_b32 v33, v18, s80, v9
	v_ashrrev_i32_e32 v49, 31, v48
	v_bfe_u32 v9, v35, 16, 1
	v_lshl_add_u64 v[20:21], v[10:11], 0, s[90:91]
	s_lshl_b32 s100, s90, 8
	s_lshr_b32 s101, s16, 8
	s_lshl_b32 s101, s101, 20
	s_add_i32 s100, s100, s101
	s_bfe_u32 s101, s16, 0x10007
	s_lshl_b32 s101, s101, 14
	s_add_i32 s100, s100, s101
	s_bfe_u32 s101, s16, 0x20005
	s_lshl_b32 s101, s101, 12
	s_add_i32 s100, s100, s101
	v_lshrrev_b32_e32 v62, 5, v146
	v_lshlrev_b32_e32 v62, 5, v62
	v_lshlrev_b32_e32 v64, 4, v146
	v_xor_b32_e32 v62, v62, v64
	v_add_u32_e32 v62, s100, v62
	v_mov_b32_e32 v63, v19
	v_sub_u32_e32 v68, 0, v8
	v_ashrrev_i32_e32 v69, 31, v68
	v_lshl_add_u64 v[66:67], v[10:11], 0, v[68:69]
	v_lshl_add_u64 v[68:69], v[66:67], 0, v[62:63]
	v_lshlrev_b64 v[48:49], 12, v[48:49]
	v_add3_u32 v9, v35, v9, s79
	v_bfe_u32 v18, v23, 16, 1
	v_lshl_add_u64 v[48:49], v[20:21], 0, v[48:49]
	v_lshrrev_b32_e32 v9, 16, v9
	v_add3_u32 v18, v23, v18, s79
	global_store_dwordx4 v[68:69], v[30:33], off nt
	v_add_u32_e32 v22, s16, v27
	v_ashrrev_i32_e32 v23, 31, v22
	v_and_or_b32 v30, v18, s80, v9
	v_bfe_u32 v9, v37, 16, 1
	v_add3_u32 v9, v37, v9, s79
	v_bfe_u32 v18, v39, 16, 1
	v_lshrrev_b32_e32 v9, 16, v9
	v_add3_u32 v18, v39, v18, s79
	v_and_or_b32 v31, v18, s80, v9
	v_bfe_u32 v9, v41, 16, 1
	v_add3_u32 v9, v41, v9, s79
	v_bfe_u32 v18, v43, 16, 1
	v_lshrrev_b32_e32 v9, 16, v9
	v_add3_u32 v18, v43, v18, s79
	v_and_or_b32 v32, v18, s80, v9
	v_bfe_u32 v9, v45, 16, 1
	v_add3_u32 v9, v45, v9, s79
	v_bfe_u32 v18, v47, 16, 1
	v_lshrrev_b32_e32 v9, 16, v9
	v_add3_u32 v18, v47, v18, s79
	v_lshlrev_b64 v[22:23], 12, v[22:23]
	v_and_or_b32 v33, v18, s80, v9
	v_lshl_add_u64 v[22:23], v[20:21], 0, v[22:23]
	global_store_dwordx4 v[68:69], v[30:33], off offset:2048 nt
	ds_read2_b32 v[22:23], v71 offset0:33 offset1:37
	ds_read2_b32 v[34:35], v71 offset1:4
	ds_read2_b32 v[36:37], v71 offset0:66 offset1:70
	ds_read2_b32 v[38:39], v71 offset0:99 offset1:103
	ds_read2_b32 v[40:41], v71 offset0:132 offset1:136
	ds_read2_b32 v[42:43], v71 offset0:165 offset1:169
	ds_read2_b32 v[44:45], v71 offset0:198 offset1:202
	ds_read2_b32 v[46:47], v71 offset0:231 offset1:235
	s_waitcnt lgkmcnt(7)
	v_bfe_u32 v18, v22, 16, 1
	s_waitcnt lgkmcnt(6)
	v_bfe_u32 v9, v34, 16, 1
	v_add3_u32 v9, v34, v9, s79
	v_lshrrev_b32_e32 v9, 16, v9
	v_add3_u32 v18, v22, v18, s79
	v_and_or_b32 v30, v18, s80, v9
	s_waitcnt lgkmcnt(5)
	v_bfe_u32 v9, v36, 16, 1
	v_add3_u32 v9, v36, v9, s79
	s_waitcnt lgkmcnt(4)
	v_bfe_u32 v18, v38, 16, 1
	v_lshrrev_b32_e32 v9, 16, v9
	v_add3_u32 v18, v38, v18, s79
	v_and_or_b32 v31, v18, s80, v9
	s_waitcnt lgkmcnt(3)
	v_bfe_u32 v9, v40, 16, 1
	v_add3_u32 v9, v40, v9, s79
	s_waitcnt lgkmcnt(2)
	v_bfe_u32 v18, v42, 16, 1
	v_lshrrev_b32_e32 v9, 16, v9
	v_add3_u32 v18, v42, v18, s79
	v_and_or_b32 v32, v18, s80, v9
	s_waitcnt lgkmcnt(1)
	v_bfe_u32 v9, v44, 16, 1
	v_add3_u32 v9, v44, v9, s79
	s_waitcnt lgkmcnt(0)
	v_bfe_u32 v18, v46, 16, 1
	v_lshrrev_b32_e32 v9, 16, v9
	v_add3_u32 v18, v46, v18, s79
	v_add_u32_e32 v48, s16, v28
	v_and_or_b32 v33, v18, s80, v9
	v_ashrrev_i32_e32 v49, 31, v48
	v_bfe_u32 v9, v35, 16, 1
	v_lshlrev_b64 v[48:49], 12, v[48:49]
	v_add3_u32 v9, v35, v9, s79
	v_bfe_u32 v18, v23, 16, 1
	v_lshl_add_u64 v[48:49], v[20:21], 0, v[48:49]
	v_lshrrev_b32_e32 v9, 16, v9
	v_add3_u32 v18, v23, v18, s79
	global_store_dwordx4 v[68:69], v[30:33], off offset:1024 nt
	v_add_u32_e32 v22, s16, v29
	v_ashrrev_i32_e32 v23, 31, v22
	v_and_or_b32 v30, v18, s80, v9
	v_bfe_u32 v9, v37, 16, 1
	v_add3_u32 v9, v37, v9, s79
	v_bfe_u32 v18, v39, 16, 1
	v_lshrrev_b32_e32 v9, 16, v9
	v_add3_u32 v18, v39, v18, s79
	v_and_or_b32 v31, v18, s80, v9
	v_bfe_u32 v9, v41, 16, 1
	v_add3_u32 v9, v41, v9, s79
	v_bfe_u32 v18, v43, 16, 1
	v_lshrrev_b32_e32 v9, 16, v9
	v_add3_u32 v18, v43, v18, s79
	v_and_or_b32 v32, v18, s80, v9
	v_bfe_u32 v9, v45, 16, 1
	v_add3_u32 v9, v45, v9, s79
	v_bfe_u32 v18, v47, 16, 1
	v_lshrrev_b32_e32 v9, 16, v9
	v_add3_u32 v18, v47, v18, s79
	v_lshlrev_b64 v[22:23], 12, v[22:23]
	v_and_or_b32 v33, v18, s80, v9
	v_lshl_add_u64 v[20:21], v[20:21], 0, v[22:23]
	global_store_dwordx4 v[68:69], v[30:33], off offset:3072 nt
	s_waitcnt lgkmcnt(0)
